# rw_scan: + tl-block constant reads hoisted to stage start with def-use renaming, bonus-block drains removed, flush LDS read hoisted
# baseline (speedup 1.0000x reference)
; #define LAS __attribute__((address_space(3)))
; __device__ __forceinline__ f32x4 mma16(bf16x8 a, bf16x8 b, f32x4 c) { return __builtin_amdgcn_mfma_f32_16x16x32_bf16(a, b, c, 0, 0, 0); }
; __device__ __forceinline__ void rw_scan(LAS unsigned char* L, const bf16_t* Rg, const bf16_t* Kg, const bf16_t* Vg, const bf16_t* VF, const bf16_t* LO, const bf16_t* wlbT, const bf16_t* albT, const bf16_t* vlbT, ...
;     ...
;                 f32x4 accw[2], acca[2], accv = (f32x4){0.f, 0.f, 0.f, 0.f};
; #pragma unroll
;                 for (int tl = 0; tl < 2; ++tl) { const int td = 2 * half + tl; accw[tl] = (f32x4){0.f, 0.f, 0.f, 0.f}; acca[tl] = (f32x4){0.f, 0.f, 0.f, 0.f};
;                     accw[tl] = mma16(lfrag(BTw, 72, td * 16 + fr, 8 * fq), flw0, accw[tl]); accw[tl] = mma16(lfrag(BTw, 72, td * 16 + fr, 32 + 8 * fq), flw1, accw[tl]);
;                     acca[tl] = mma16(lfrag(BTa, 72, td * 16 + fr, 8 * fq), fla0, acca[tl]); acca[tl] = mma16(lfrag(BTa, 72, td * 16 + fr, 32 + 8 * fq), fla1, acca[tl]); }
;                 if (hasvf && hasv) accv = mma16(lfrag(BTv, 40, q * 16 + fr, 8 * fq), flv, accv);
;                 float n2 = 0.f;
; #pragma unroll
;                 for (int td = 0; td < 4; ++td) { const f32x4 kk_ = unpk4(xK[td]) * *(const LAS f32x4*)(CSTb + 192 + td * 16 + 4 * fq); n2 += (kk_[0] * kk_[0] + kk_[1] * kk_[1]) + (kk_[2] * kk_[2] + kk_[3] * kk_[3]); }
;                 n2 += __shfl_xor(n2, 16); n2 += __shfl_xor(n2, 32);
;                 const float inv = fminf(__builtin_amdgcn_rsqf(n2), 1e12f);
;                 const f32x4 krs0 = unpk4(half ? xK[2] : xK[0]), krs1 = unpk4(half ? xK[3] : xK[1]), r4s0 = unpk4(xR[0]), r4s1 = unpk4(xR[1]); const f32x4 v4u = unpk4(xV), vf4u = unpk4(xVF);
;                 asm volatile("" ::: "memory");
;                 if (m + 1 < 256) RW_LOADS(m + 1);
;     ...
;             if (m >= 2) {
;                 const LAS bf16_t* ob = OUTb + (m & 1) * (64 * 18);
;                 const int i = tid >> 3, rr = (tid & 7) * 2; const int st = 64 * (m - 2) + i, t = g ? (S_ - 1 - st) : st; const size_t row = (size_t)b * S_ + t;
;                 *(unsigned*)(WKV + ((size_t)g * T_ + row) * 1024 + h * 64 + 16 * q + rr) = *(const LAS unsigned*)(ob + i * 18 + rr);
.LBB0_95:
	s_or_b64 exec, exec, s[22:23]
	ds_read_b32 v250, v143 offset:48640
	s_cmpk_lt_u32 s81, 0x100
	s_cselect_b64 s[24:25], -1, 0
	s_cmpk_gt_u32 s81, 0xff
	s_cbranch_scc1 .LBB0_119
	v_add_u32_e32 v1, v66, v224
	ds_read_b128 v[212:215], v68
	ds_read_b128 v[216:219], v68 offset:64
	ds_read_b128 v[230:233], v68 offset:9216
	ds_read_b128 v[234:237], v68 offset:9280
	ds_read_b128 v[238:241], v68 offset:2304
	ds_read_b128 v[246:249], v68 offset:2368
	ds_read_b128 v[112:115], v68 offset:11520
	ds_read_b128 v[116:119], v68 offset:11584
	ds_read_b128 v[120:123], v66 offset:24320
	ds_read_b128 v[202:205], v66 offset:24384
	ds_read_b128 v[206:209], v66 offset:24448
	ds_read_b128 v[102:105], v66 offset:24512
	ds_read_b128 v[126:129], v69 offset:23552
	ds_read_b128 v[130:133], v69 offset:24064
	s_waitcnt vmcnt(9) lgkmcnt(13)
	v_mfma_f32_16x16x32_bf16 v[40:43], v[212:215], v[20:23], 0
	ds_read_b128 v[212:215], v1 offset:18432
	s_waitcnt vmcnt(8) lgkmcnt(13)
	v_mfma_f32_16x16x32_bf16 v[56:59], v[216:219], v[16:19], v[40:43]
	s_waitcnt vmcnt(7) lgkmcnt(12)
	v_mfma_f32_16x16x32_bf16 v[40:43], v[230:233], v[12:15], 0
	s_waitcnt vmcnt(6) lgkmcnt(11)
	v_mfma_f32_16x16x32_bf16 v[52:55], v[234:237], v[8:11], v[40:43]
	s_waitcnt lgkmcnt(10)
	v_mfma_f32_16x16x32_bf16 v[20:23], v[238:241], v[20:23], 0
	s_waitcnt lgkmcnt(9)
	v_mfma_f32_16x16x32_bf16 v[48:51], v[246:249], v[16:19], v[20:23]
	s_waitcnt lgkmcnt(8)
	v_mfma_f32_16x16x32_bf16 v[12:15], v[112:115], v[12:15], 0
	s_waitcnt lgkmcnt(7)
	v_mfma_f32_16x16x32_bf16 v[44:47], v[116:119], v[8:11], v[12:15]
	ds_read_b128 v[216:219], v69 offset:24320
	ds_read_b128 v[230:233], v69 offset:24576
	ds_read_b128 v[234:237], v69 offset:24832
	ds_read_b128 v[238:241], v69 offset:23616
	ds_read_b128 v[246:249], v69 offset:24128
	v_mov_b32_e32 v40, 0
	v_mov_b32_e32 v41, 0
	v_mov_b32_e32 v42, 0
	v_mov_b32_e32 v43, 0
	s_and_saveexec_b64 s[22:23], s[40:41]
	s_cbranch_execz .LBB0_98
	s_waitcnt lgkmcnt(5)
	v_mfma_f32_16x16x32_bf16 v[40:43], v[212:215], v[4:7], 0
.LBB0_98:
	s_or_b64 exec, exec, s[22:23]
	ds_read_b128 v[212:215], v69 offset:24384
	s_waitcnt vmcnt(5)
	v_lshlrev_b32_e32 v2, 16, v106
	v_and_b32_e32 v3, 0xffff0000, v106
	v_lshlrev_b32_e32 v12, 16, v107
	v_and_b32_e32 v13, 0xffff0000, v107
	s_waitcnt lgkmcnt(6)
	v_pk_mul_f32 v[2:3], v[120:121], v[2:3]
	v_pk_mul_f32 v[10:11], v[122:123], v[12:13]
	v_mul_f32_e32 v1, v3, v3
	v_fmac_f32_e32 v1, v2, v2
	v_mul_f32_e32 v2, v11, v11
	v_fmac_f32_e32 v2, v10, v10
	v_add_f32_e32 v1, v1, v2
	s_waitcnt vmcnt(4)
	v_lshlrev_b32_e32 v2, 16, v96
	v_and_b32_e32 v3, 0xffff0000, v96
	v_lshlrev_b32_e32 v12, 16, v97
	v_and_b32_e32 v13, 0xffff0000, v97
	s_nop 0
	v_pk_mul_f32 v[2:3], v[202:203], v[2:3]
	v_pk_mul_f32 v[10:11], v[204:205], v[12:13]
	v_mul_f32_e32 v3, v3, v3
	v_fmac_f32_e32 v3, v2, v2
	v_mul_f32_e32 v2, v11, v11
	v_fmac_f32_e32 v2, v10, v10
	v_add_f32_e32 v2, v3, v2
	v_add_f32_e32 v1, v1, v2
	s_waitcnt vmcnt(3)
	v_lshlrev_b32_e32 v2, 16, v110
	v_and_b32_e32 v3, 0xffff0000, v110
	v_lshlrev_b32_e32 v12, 16, v111
	v_and_b32_e32 v13, 0xffff0000, v111
	s_nop 0
	v_pk_mul_f32 v[2:3], v[206:207], v[2:3]
	v_pk_mul_f32 v[10:11], v[208:209], v[12:13]
	v_mul_f32_e32 v3, v3, v3
	v_fmac_f32_e32 v3, v2, v2
	v_mul_f32_e32 v2, v11, v11
	v_fmac_f32_e32 v2, v10, v10
	v_add_f32_e32 v2, v3, v2
	v_add_f32_e32 v1, v1, v2
	s_waitcnt vmcnt(2)
	v_lshlrev_b32_e32 v2, 16, v100
	v_and_b32_e32 v3, 0xffff0000, v100
	v_lshlrev_b32_e32 v12, 16, v101
	v_and_b32_e32 v13, 0xffff0000, v101
	s_nop 0
	v_pk_mul_f32 v[2:3], v[102:103], v[2:3]
	v_pk_mul_f32 v[10:11], v[104:105], v[12:13]
	v_mul_f32_e32 v3, v3, v3
	v_fmac_f32_e32 v3, v2, v2
	v_mul_f32_e32 v2, v11, v11
	v_fmac_f32_e32 v2, v10, v10
	v_add_f32_e32 v2, v3, v2
	v_and_b32_e32 v3, 64, v200
	v_add_f32_e32 v2, v1, v2
	v_xor_b32_e32 v1, 16, v200
	v_add_u32_e32 v3, 64, v3
	v_cmp_lt_i32_e32 vcc, v1, v3
	v_mov_b32_e32 v95, v0
	v_readlane_b32 s2, v251, 34
	v_cndmask_b32_e32 v1, v200, v1, vcc
	v_lshlrev_b32_e32 v1, 2, v1
	v_mov_b32_e32 v8, v2
	s_nop 1
	v_permlane16_swap_b32_e32 v2, v8
	v_readlane_b32 s3, v251, 35
	v_mov_b32_e32 v75, v0
	v_add_f32_e32 v225, v2, v8
	v_xor_b32_e32 v2, 32, v200
	v_cmp_lt_i32_e32 vcc, v2, v3
	s_nop 1
	v_cndmask_b32_e32 v2, v200, v2, vcc
	v_lshlrev_b32_e32 v73, 2, v2
	v_lshl_or_b32 v2, s81, 6, v141
	v_sub_u32_e32 v3, 0x3fff, v2
	v_cndmask_b32_e64 v2, v3, v2, s[70:71]
	v_or_b32_e32 v94, s38, v2
	v_lshlrev_b64 v[2:3], 10, v[94:95]
	v_lshl_add_u64 v[102:103], s[2:3], 0, v[2:3]
	v_lshl_add_u64 v[8:9], s[20:21], 1, v[102:103]
	v_lshl_add_u64 v[8:9], v[8:9], 0, v[74:75]
	global_load_dwordx4 v[20:23], v[8:9], off
	global_load_dwordx4 v[16:19], v[8:9], off offset:64
	global_load_dwordx4 v[12:15], v[8:9], off offset:256
	s_nop 0
	global_load_dwordx4 v[8:11], v[8:9], off offset:320
	v_mov_b32_e32 v226, v225
	s_nop 1
	v_permlane32_swap_b32_e32 v225, v226
	s_and_saveexec_b64 s[22:23], s[40:41]
	s_cbranch_execz .LBB0_100
	v_lshl_add_u64 v[4:5], v[102:103], 0, v[74:75]
	global_load_dwordx4 v[4:7], v[4:5], off offset:832

; #define LAS __attribute__((address_space(3)))
; __device__ __forceinline__ f32x4 sigm4(f32x4 x) { return (f32x4){sigm(x[0]), sigm(x[1]), sigm(x[2]), sigm(x[3])}; }
; template <int CTRL> __device__ __forceinline__ float dpp0(float x) { return __builtin_bit_cast(float, __builtin_amdgcn_update_dpp(0, __builtin_bit_cast(int, x), CTRL, 0xf, 0xf, true)); }
; __device__ __forceinline__ float row16_scan(float x) { x += dpp0<0x111>(x); x += dpp0<0x112>(x); x += dpp0<0x114>(x); x += dpp0<0x118>(x); return x; }
; __device__ __forceinline__ void rw_scan(LAS unsigned char* L, const bf16_t* Rg, const bf16_t* Kg, const bf16_t* Vg, const bf16_t* VF, const bf16_t* LO, const bf16_t* wlbT, const bf16_t* albT, const bf16_t* vlbT, ...
;     ...
;                 float bs = 0.f;
; #pragma unroll
;                 for (int tl = 0; tl < 2; ++tl) { const int td = 2 * half + tl; const int c4 = td * 16 + 4 * fq;
;                     const f32x4 lw = sigm4(*(const LAS f32x4*)(CSTb + c4) + accw[tl]) * (-0.6065306597126334f * 1.4426950408889634f);
;                     f32x4 cl;
; #pragma unroll
;                     for (int r = 0; r < 4; ++r) cl[r] = row16_scan(lw[r]);
;                     const f32x4 ep = (f32x4){__builtin_amdgcn_exp2f(cl[0]), __builtin_amdgcn_exp2f(cl[1]), __builtin_amdgcn_exp2f(cl[2]), __builtin_amdgcn_exp2f(cl[3])};
;                     f32x4 epL, em, en;
; #pragma unroll
;                     for (int r = 0; r < 4; ++r) { epL[r] = __shfl(ep[r], (lane & 48) | 15); const float sh = dpp0<0x111>(ep[r]); em[r] = (fr == 0) ? 1.f : sh; en[r] = __builtin_amdgcn_rcpf(ep[r]); }
;                     const f32x4 eL = epL * en;
;                     const f32x4 a4 = sigm4(*(const LAS f32x4*)(CSTb + 128 + c4) + acca[tl]);
;                     const f32x4 kr = tl ? krs1 : krs0; const f32x4 kk4 = kr * *(const LAS f32x4*)(CSTb + 192 + c4) * inv;
;                     const f32x4 kd4 = kr * (1.f + (a4 - 1.f) * *(const LAS f32x4*)(CSTb + 256 + c4)); const f32x4 b4 = kk4 * a4; const f32x4 r4 = tl ? r4s1 : r4s0;
;                     if (ti == q) { const f32x4 rk = r4 * kd4 * *(const LAS f32x4*)(CSTb + 320 + c4); bs += (rk[0] + rk[1]) + (rk[2] + rk[3]); }
.LBB0_103:
	s_or_b64 exec, exec, s[22:23]
	v_cndmask_b32_e64 v2, v111, v107, s[46:47]
	v_cndmask_b32_e64 v3, v110, v106, s[46:47]
	v_lshlrev_b32_e32 v124, 16, v2
	v_and_b32_e32 v125, 0xffff0000, v2
	v_and_or_b32 v2, v200, 64, v64
	s_waitcnt lgkmcnt(1)
	v_pk_add_f32 v[56:57], v[56:57], v[126:127]
	v_lshlrev_b32_e32 v110, 16, v3
	v_and_b32_e32 v111, 0xffff0000, v3
	v_lshl_or_b32 v3, v2, 2, 60
	v_mul_f32_e32 v2, 0xbfb8aa3b, v56
	v_exp_f32_e32 v2, v2
	v_mul_f32_e32 v56, 0xbfb8aa3b, v57
	v_exp_f32_e32 v75, v56
	v_pk_add_f32 v[56:57], v[58:59], v[128:129]
	v_add_f32_e32 v2, 1.0, v2
	v_rcp_f32_e32 v2, v2
	v_mul_f32_e32 v56, 0xbfb8aa3b, v56
	v_exp_f32_e32 v56, v56
	v_add_f32_e32 v58, 1.0, v75
	v_mul_f32_e32 v57, 0xbfb8aa3b, v57
	v_rcp_f32_e32 v58, v58
	v_exp_f32_e32 v57, v57
	v_mul_f32_e32 v59, 0xbf60028a, v2
	v_add_f32_e32 v56, 1.0, v56
	v_rcp_f32_e32 v56, v56
	v_mov_b32_dpp v59, v59 row_shr:1 row_mask:0xf bank_mask:0xf bound_ctrl:1
	v_fmac_f32_e32 v59, 0xbf60028a, v2
	v_add_f32_e32 v57, 1.0, v57
	v_rcp_f32_e32 v57, v57
	v_add_f32_dpp v2, v59, v59 row_shr:2 row_mask:0xf bank_mask:0xf bound_ctrl:1
	v_mul_f32_e32 v59, 0xbf60028a, v58
	s_waitcnt lgkmcnt(0)
	v_pk_add_f32 v[52:53], v[52:53], v[130:131]
	v_add_f32_dpp v2, v2, v2 row_shr:4 row_mask:0xf bank_mask:0xf bound_ctrl:1
	v_mov_b32_dpp v59, v59 row_shr:1 row_mask:0xf bank_mask:0xf bound_ctrl:1
	v_fmac_f32_e32 v59, 0xbf60028a, v58
	v_mul_f32_e32 v52, 0xbfb8aa3b, v52
	v_add_f32_dpp v2, v2, v2 row_shr:8 row_mask:0xf bank_mask:0xf bound_ctrl:1
	v_add_f32_dpp v58, v59, v59 row_shr:2 row_mask:0xf bank_mask:0xf bound_ctrl:1
	v_mul_f32_e32 v59, 0xbf60028a, v56
	v_exp_f32_e32 v126, v2
	v_add_f32_dpp v58, v58, v58 row_shr:4 row_mask:0xf bank_mask:0xf bound_ctrl:1
	v_mov_b32_dpp v59, v59 row_shr:1 row_mask:0xf bank_mask:0xf bound_ctrl:1
	v_fmac_f32_e32 v59, 0xbf60028a, v56
	v_add_f32_dpp v58, v58, v58 row_shr:8 row_mask:0xf bank_mask:0xf bound_ctrl:1
	v_exp_f32_e32 v127, v58
	v_add_f32_dpp v56, v59, v59 row_shr:2 row_mask:0xf bank_mask:0xf bound_ctrl:1
	v_mul_f32_e32 v59, 0xbf60028a, v57
	v_lshlrev_b32_e32 v106, 16, v108
	v_add_f32_dpp v56, v56, v56 row_shr:4 row_mask:0xf bank_mask:0xf bound_ctrl:1
	v_mov_b32_dpp v59, v59 row_shr:1 row_mask:0xf bank_mask:0xf bound_ctrl:1
	v_fmac_f32_e32 v59, 0xbf60028a, v57
	v_add_f32_dpp v56, v56, v56 row_shr:8 row_mask:0xf bank_mask:0xf bound_ctrl:1
	v_exp_f32_e32 v128, v56
	v_add_f32_dpp v57, v59, v59 row_shr:2 row_mask:0xf bank_mask:0xf bound_ctrl:1
	v_exp_f32_e32 v59, v52
	v_mul_f32_e32 v52, 0xbfb8aa3b, v53
	v_exp_f32_e32 v75, v52
	v_pk_add_f32 v[52:53], v[54:55], v[132:133]
	v_add_f32_dpp v57, v57, v57 row_shr:4 row_mask:0xf bank_mask:0xf bound_ctrl:1
	v_mul_f32_e32 v52, 0xbfb8aa3b, v52
	v_exp_f32_e32 v52, v52
	v_mul_f32_e32 v53, 0xbfb8aa3b, v53
	v_exp_f32_e32 v53, v53
	v_add_f32_dpp v57, v57, v57 row_shr:8 row_mask:0xf bank_mask:0xf bound_ctrl:1
	v_exp_f32_e32 v129, v57
	v_add_f32_e32 v54, 1.0, v59
	v_add_f32_e32 v52, 1.0, v52
	v_rcp_f32_e32 v134, v54
	v_add_f32_e32 v54, 1.0, v75
	v_rcp_f32_e32 v136, v52
	v_add_f32_e32 v52, 1.0, v53
	v_rcp_f32_e32 v135, v54
	v_rcp_f32_e32 v137, v52
	ds_bpermute_b32 v56, v3, v126
	ds_bpermute_b32 v57, v3, v127
	ds_bpermute_b32 v58, v3, v128
	ds_bpermute_b32 v59, v3, v129
	v_pk_add_f32 v[198:199], v[136:137], -1.0 op_sel_hi:[1,0]
	v_pk_add_f32 v[202:203], v[134:135], -1.0 op_sel_hi:[1,0]
	s_waitcnt lgkmcnt(4)
	v_pk_fma_f32 v[132:133], v[232:233], v[198:199], 1.0 op_sel_hi:[1,1,0]
	v_pk_fma_f32 v[198:199], v[230:231], v[202:203], 1.0 op_sel_hi:[1,1,0]
	v_and_b32_e32 v107, 0xffff0000, v108
	v_lshlrev_b32_e32 v108, 16, v109
	v_and_b32_e32 v109, 0xffff0000, v109
	v_mov_b32_dpp v2, v126 row_shr:1 row_mask:0xf bank_mask:0xf bound_ctrl:1
	v_mov_b32_dpp v228, v127 row_shr:1 row_mask:0xf bank_mask:0xf bound_ctrl:1
	v_mov_b32_dpp v227, v128 row_shr:1 row_mask:0xf bank_mask:0xf bound_ctrl:1
	v_mov_b32_dpp v229, v129 row_shr:1 row_mask:0xf bank_mask:0xf bound_ctrl:1
	v_pk_mul_f32 v[130:131], v[132:133], v[124:125]
	v_pk_mul_f32 v[132:133], v[198:199], v[110:111]
	v_mov_b32_e32 v75, 0
	s_and_saveexec_b64 s[22:23], s[72:73]
	s_cbranch_execz .LBB0_105
	v_pk_mul_f32 v[198:199], v[130:131], v[108:109]
	v_pk_mul_f32 v[202:203], v[132:133], v[106:107]
	v_pk_mul_f32 v[198:199], v[198:199], v[236:237]
	v_pk_mul_f32 v[202:203], v[202:203], v[234:235]
	s_nop 0
	v_pk_mov_b32 v[204:205], v[202:203], v[198:199] op_sel:[1,0]
	v_mov_b32_e32 v203, v199
	v_pk_add_f32 v[198:199], v[204:205], v[202:203]
	s_nop 0
	v_add_f32_e32 v75, v198, v199
	v_add_f32_e32 v75, 0, v75
; #define LAS __attribute__((address_space(3)))
; __device__ __forceinline__ void rw_scan(LAS unsigned char* L, const bf16_t* Rg, const bf16_t* Kg, const bf16_t* Vg, const bf16_t* VF, const bf16_t* LO, const bf16_t* wlbT, const bf16_t* albT, const bf16_t* vlbT, ...
;     ...
;                 for (int tl = 0; tl < 2; ++tl) { const int td = 2 * half + tl; const int c4 = td * 16 + 4 * fq;
;                     const f32x4 lw = sigm4(*(const LAS f32x4*)(CSTb + c4) + accw[tl]) * (-0.6065306597126334f * 1.4426950408889634f);
;                     f32x4 cl;
; #pragma unroll
;                     for (int r = 0; r < 4; ++r) cl[r] = row16_scan(lw[r]);
;                     const f32x4 ep = (f32x4){__builtin_amdgcn_exp2f(cl[0]), __builtin_amdgcn_exp2f(cl[1]), __builtin_amdgcn_exp2f(cl[2]), __builtin_amdgcn_exp2f(cl[3])};
;                     f32x4 epL, em, en;
; #pragma unroll
;                     for (int r = 0; r < 4; ++r) { epL[r] = __shfl(ep[r], (lane & 48) | 15); const float sh = dpp0<0x111>(ep[r]); em[r] = (fr == 0) ? 1.f : sh; en[r] = __builtin_amdgcn_rcpf(ep[r]); }
;                     const f32x4 eL = epL * en;
;                     const f32x4 a4 = sigm4(*(const LAS f32x4*)(CSTb + 128 + c4) + acca[tl]);
;                     const f32x4 kr = tl ? krs1 : krs0; const f32x4 kk4 = kr * *(const LAS f32x4*)(CSTb + 192 + c4) * inv;
;                     const f32x4 kd4 = kr * (1.f + (a4 - 1.f) * *(const LAS f32x4*)(CSTb + 256 + c4)); const f32x4 b4 = kk4 * a4; const f32x4 r4 = tl ? r4s1 : r4s0;
;                     if (ti == q) { const f32x4 rk = r4 * kd4 * *(const LAS f32x4*)(CSTb + 320 + c4); bs += (rk[0] + rk[1]) + (rk[2] + rk[3]); }
;                     const int p4 = 32 * (td >> 1) + 8 * fq + 4 * (td & 1);
;                     *(LAS u32x2*)(KQ + irow * 72 + p4) = pk4(kk4 * em); *(LAS u32x2*)(RQ + irow * 72 + p4) = pk4(r4 * ep);
;                     *(LAS u32x2*)(BD + irow * 72 + p4) = pk4(b4 * en); *(LAS u32x2*)(KD + irow * 72 + p4) = pk4(kd4 * en);
;                     const f32x4 bl = b4 * eL, kl = kd4 * eL;
; #pragma unroll
;                     for (int r = 0; r < 4; ++r) *(LAS unsigned*)(W2 + (c4 + r) * 136 + ti * 32 + 8 * (fr >> 2) + 2 * (fr & 3)) = cvt_pk_bf16(bl[r], kl[r]);
;                     if (fr == 15) *(LAS f32x4*)(LLs + ti * 64 + c4) = epL;
.LBB0_105:
	s_or_b64 exec, exec, s[22:23]
	v_add_f32_e32 v198, v225, v226
	v_rsq_f32_e32 v203, v198
	v_cndmask_b32_e64 v198, v2, 1.0, s[58:59]
	v_pk_mul_f32 v[54:55], v[218:219], v[124:125]
	v_pk_mul_f32 v[52:53], v[216:217], v[110:111]
	v_min_f32_e32 v2, 0x5368d4a5, v203
	v_rcp_f32_e32 v202, v126
	v_cndmask_b32_e64 v199, v228, 1.0, s[58:59]
	v_rcp_f32_e32 v203, v127
	v_rcp_f32_e32 v204, v128
	v_rcp_f32_e32 v205, v129
	v_cndmask_b32_e64 v206, v227, 1.0, s[58:59]
	v_cndmask_b32_e64 v207, v229, 1.0, s[58:59]
	v_pk_mul_f32 v[54:55], v[2:3], v[54:55] op_sel_hi:[0,1]
	v_pk_mul_f32 v[52:53], v[2:3], v[52:53] op_sel_hi:[0,1]
	v_pk_mul_f32 v[110:111], v[52:53], v[134:135]
	v_pk_mul_f32 v[124:125], v[54:55], v[136:137]
	v_pk_mul_f32 v[54:55], v[206:207], v[54:55]
	v_pk_mul_f32 v[52:53], v[198:199], v[52:53]
	v_pk_mul_f32 v[106:107], v[126:127], v[106:107]
	v_cvt_pk_bf16_f32 v52, v52, v53
	v_cvt_pk_bf16_f32 v53, v54, v55
	v_pk_mul_f32 v[54:55], v[128:129], v[108:109]
	v_cvt_pk_bf16_f32 v106, v106, v107
	v_cvt_pk_bf16_f32 v107, v54, v55
	ds_write2st64_b64 v145, v[52:53], v[106:107] offset0:104 offset1:122
	v_pk_mul_f32 v[52:53], v[204:205], v[124:125]
	v_pk_mul_f32 v[54:55], v[202:203], v[110:111]
	v_pk_mul_f32 v[106:107], v[202:203], v[132:133]
	v_cvt_pk_bf16_f32 v54, v54, v55
	v_cvt_pk_bf16_f32 v55, v52, v53
	v_pk_mul_f32 v[52:53], v[204:205], v[130:131]
	s_waitcnt lgkmcnt(3)
	v_pk_mul_f32 v[208:209], v[202:203], v[56:57]
	s_waitcnt lgkmcnt(1)
	v_pk_mul_f32 v[210:211], v[204:205], v[58:59]
	v_cvt_pk_bf16_f32 v106, v106, v107
	v_cvt_pk_bf16_f32 v107, v52, v53
	ds_write2st64_b64 v145, v[54:55], v[106:107] offset0:49 offset1:67
	v_pk_mul_f32 v[52:53], v[210:211], v[124:125]
	v_pk_mul_f32 v[54:55], v[208:209], v[110:111]
	v_pk_mul_f32 v[106:107], v[210:211], v[130:131]
	v_pk_mul_f32 v[108:109], v[208:209], v[132:133]
	v_cvt_pk_bf16_f32 v52, v52, v106
	v_cvt_pk_bf16_f32 v54, v54, v108
	v_cvt_pk_bf16_f32 v55, v55, v109
	v_cvt_pk_bf16_f32 v53, v53, v107
	ds_write2_b32 v195, v54, v55 offset1:68
	ds_write2_b32 v195, v52, v53 offset0:136 offset1:204
	s_and_saveexec_b64 s[22:23], s[60:61]
	ds_write_b128 v175, v[56:59]
	s_or_b64 exec, exec, s[22:23]
	ds_read_b128 v[216:219], v69 offset:24640
	ds_read_b128 v[230:233], v69 offset:24896
	v_cndmask_b32_e64 v53, v100, v96, s[46:47]
	v_cndmask_b32_e64 v52, v101, v97, s[46:47]
	v_lshlrev_b32_e32 v56, 16, v53
	v_pk_add_f32 v[48:49], v[48:49], v[238:239]
	v_pk_add_f32 v[44:45], v[44:45], v[246:247]
	v_mul_f32_e32 v48, 0xbfb8aa3b, v48
	v_exp_f32_e32 v96, v48
	v_mul_f32_e32 v48, 0xbfb8aa3b, v49
	v_exp_f32_e32 v97, v48
	v_pk_add_f32 v[48:49], v[50:51], v[240:241]
	v_add_f32_e32 v50, 1.0, v96
	v_rcp_f32_e32 v50, v50
	v_mul_f32_e32 v48, 0xbfb8aa3b, v48
	v_add_f32_e32 v51, 1.0, v97
	v_exp_f32_e32 v48, v48
	v_rcp_f32_e32 v51, v51
	v_mul_f32_e32 v49, 0xbfb8aa3b, v49
	v_mul_f32_e32 v96, 0xbf60028a, v50
	v_exp_f32_e32 v49, v49
	v_add_f32_e32 v48, 1.0, v48
	v_mov_b32_dpp v96, v96 row_shr:1 row_mask:0xf bank_mask:0xf bound_ctrl:1
	v_fmac_f32_e32 v96, 0xbf60028a, v50
	v_rcp_f32_e32 v48, v48
	v_add_f32_e32 v49, 1.0, v49
	v_add_f32_dpp v50, v96, v96 row_shr:2 row_mask:0xf bank_mask:0xf bound_ctrl:1
	v_mul_f32_e32 v96, 0xbf60028a, v51
	v_rcp_f32_e32 v49, v49
	v_mul_f32_e32 v44, 0xbfb8aa3b, v44
	v_mov_b32_dpp v96, v96 row_shr:1 row_mask:0xf bank_mask:0xf bound_ctrl:1
	v_fmac_f32_e32 v96, 0xbf60028a, v51
	v_add_f32_dpp v50, v50, v50 row_shr:4 row_mask:0xf bank_mask:0xf bound_ctrl:1
	v_and_b32_e32 v57, 0xffff0000, v53
	v_add_f32_dpp v51, v96, v96 row_shr:2 row_mask:0xf bank_mask:0xf bound_ctrl:1
	v_mul_f32_e32 v96, 0xbf60028a, v48
	v_add_f32_dpp v50, v50, v50 row_shr:8 row_mask:0xf bank_mask:0xf bound_ctrl:1
	v_add_f32_dpp v51, v51, v51 row_shr:4 row_mask:0xf bank_mask:0xf bound_ctrl:1
	v_mov_b32_dpp v96, v96 row_shr:1 row_mask:0xf bank_mask:0xf bound_ctrl:1
	v_fmac_f32_e32 v96, 0xbf60028a, v48
	v_add_f32_dpp v51, v51, v51 row_shr:8 row_mask:0xf bank_mask:0xf bound_ctrl:1
	v_exp_f32_e32 v97, v51
	v_exp_f32_e32 v51, v44
	v_mul_f32_e32 v44, 0xbfb8aa3b, v45
	v_add_f32_dpp v48, v96, v96 row_shr:2 row_mask:0xf bank_mask:0xf bound_ctrl:1
	v_mul_f32_e32 v96, 0xbf60028a, v49
	v_exp_f32_e32 v100, v44
	v_pk_add_f32 v[44:45], v[46:47], v[248:249]
	v_mov_b32_dpp v96, v96 row_shr:1 row_mask:0xf bank_mask:0xf bound_ctrl:1
	v_mul_f32_e32 v44, 0xbfb8aa3b, v44
	v_fmac_f32_e32 v96, 0xbf60028a, v49
	v_exp_f32_e32 v44, v44
	v_mul_f32_e32 v45, 0xbfb8aa3b, v45
	v_add_f32_dpp v49, v96, v96 row_shr:2 row_mask:0xf bank_mask:0xf bound_ctrl:1
	v_exp_f32_e32 v45, v45
	v_add_f32_dpp v48, v48, v48 row_shr:4 row_mask:0xf bank_mask:0xf bound_ctrl:1
	v_add_f32_dpp v49, v49, v49 row_shr:4 row_mask:0xf bank_mask:0xf bound_ctrl:1
	v_lshlrev_b32_e32 v58, 16, v52
	v_add_f32_dpp v48, v48, v48 row_shr:8 row_mask:0xf bank_mask:0xf bound_ctrl:1
	v_add_f32_dpp v49, v49, v49 row_shr:8 row_mask:0xf bank_mask:0xf bound_ctrl:1
	v_and_b32_e32 v59, 0xffff0000, v52
	v_lshlrev_b32_e32 v52, 16, v98
	v_and_b32_e32 v53, 0xffff0000, v98
	v_lshlrev_b32_e32 v54, 16, v99
	v_and_b32_e32 v55, 0xffff0000, v99
	v_exp_f32_e32 v96, v50
	v_exp_f32_e32 v98, v48
	v_exp_f32_e32 v99, v49
	v_add_f32_e32 v46, 1.0, v51
	v_add_f32_e32 v44, 1.0, v44
	v_rcp_f32_e32 v108, v46
	v_add_f32_e32 v46, 1.0, v100
	v_rcp_f32_e32 v110, v44
	v_add_f32_e32 v44, 1.0, v45
	v_rcp_f32_e32 v109, v46
	v_rcp_f32_e32 v111, v44
	ds_bpermute_b32 v48, v3, v96
	ds_bpermute_b32 v49, v3, v97
	ds_bpermute_b32 v50, v3, v98
	ds_bpermute_b32 v51, v3, v99
	v_pk_add_f32 v[100:101], v[110:111], -1.0 op_sel_hi:[1,0]
	v_pk_add_f32 v[106:107], v[108:109], -1.0 op_sel_hi:[1,0]
	s_waitcnt lgkmcnt(4)
	v_pk_fma_f32 v[100:101], v[218:219], v[100:101], 1.0 op_sel_hi:[1,1,0]
	v_pk_fma_f32 v[106:107], v[216:217], v[106:107], 1.0 op_sel_hi:[1,1,0]
	v_mov_b32_dpp v125, v96 row_shr:1 row_mask:0xf bank_mask:0xf bound_ctrl:1
	v_mov_b32_dpp v126, v97 row_shr:1 row_mask:0xf bank_mask:0xf bound_ctrl:1
	v_mov_b32_dpp v124, v98 row_shr:1 row_mask:0xf bank_mask:0xf bound_ctrl:1
	v_mov_b32_dpp v127, v99 row_shr:1 row_mask:0xf bank_mask:0xf bound_ctrl:1
	v_pk_mul_f32 v[100:101], v[100:101], v[58:59]
	v_pk_mul_f32 v[106:107], v[106:107], v[56:57]
	s_and_saveexec_b64 s[22:23], s[72:73]
	s_cbranch_execz .LBB0_109
	v_pk_mul_f32 v[132:133], v[100:101], v[54:55]
	v_pk_mul_f32 v[134:135], v[106:107], v[52:53]
	v_pk_mul_f32 v[130:131], v[132:133], v[232:233]
	v_pk_mul_f32 v[128:129], v[134:135], v[230:231]
	s_nop 0
	v_pk_mov_b32 v[132:133], v[128:129], v[130:131] op_sel:[1,0]
	v_mov_b32_e32 v129, v131
	v_pk_add_f32 v[128:129], v[132:133], v[128:129]
	s_nop 0
	v_add_f32_e32 v3, v128, v129
	v_add_f32_e32 v75, v75, v3
; #define LAS __attribute__((address_space(3)))
; __device__ __forceinline__ unsigned cvt_pk_bf16(float lo, float hi) { const f32x2_t v = {lo, hi}; const bf16x2_t b = __builtin_convertvector(v, bf16x2_t); return __builtin_bit_cast(unsigned, b); }
; __device__ __forceinline__ u32x2 pk4(f32x4 x) { u32x2 w; w.x = cvt_pk_bf16(x[0], x[1]); w.y = cvt_pk_bf16(x[2], x[3]); return w; }
; __device__ __forceinline__ void rw_scan(LAS unsigned char* L, const bf16_t* Rg, const bf16_t* Kg, const bf16_t* Vg, const bf16_t* VF, const bf16_t* LO, const bf16_t* wlbT, const bf16_t* albT, const bf16_t* vlbT, ...
;     ...
;                     const f32x4 kr = tl ? krs1 : krs0; const f32x4 kk4 = kr * *(const LAS f32x4*)(CSTb + 192 + c4) * inv;
;                     const f32x4 kd4 = kr * (1.f + (a4 - 1.f) * *(const LAS f32x4*)(CSTb + 256 + c4)); const f32x4 b4 = kk4 * a4; const f32x4 r4 = tl ? r4s1 : r4s0;
;                     if (ti == q) { const f32x4 rk = r4 * kd4 * *(const LAS f32x4*)(CSTb + 320 + c4); bs += (rk[0] + rk[1]) + (rk[2] + rk[3]); }
;                     const int p4 = 32 * (td >> 1) + 8 * fq + 4 * (td & 1);
;                     *(LAS u32x2*)(KQ + irow * 72 + p4) = pk4(kk4 * em); *(LAS u32x2*)(RQ + irow * 72 + p4) = pk4(r4 * ep);
;                     *(LAS u32x2*)(BD + irow * 72 + p4) = pk4(b4 * en); *(LAS u32x2*)(KD + irow * 72 + p4) = pk4(kd4 * en);
;                     const f32x4 bl = b4 * eL, kl = kd4 * eL;
; #pragma unroll
;                     for (int r = 0; r < 4; ++r) *(LAS unsigned*)(W2 + (c4 + r) * 136 + ti * 32 + 8 * (fr >> 2) + 2 * (fr & 3)) = cvt_pk_bf16(bl[r], kl[r]);
;                     if (fr == 15) *(LAS f32x4*)(LLs + ti * 64 + c4) = epL;
;                 }
;                 if (ti == q) { bs += __shfl_xor(bs, 16); bs += __shfl_xor(bs, 32);
;                     if (fq == 0) BON2[((size_t)(g * 2 + half) * T_ + rowcur) * 16 + h] = bs; }
.LBB0_109:
	s_or_b64 exec, exec, s[22:23]
	v_mov_b32_e32 v3, v2
	v_pk_mul_f32 v[46:47], v[214:215], v[58:59]
	v_pk_mul_f32 v[44:45], v[212:213], v[56:57]
	v_mov_b32_e32 v56, v2
	v_mov_b32_e32 v57, v2
	v_cndmask_b32_e64 v128, v125, 1.0, s[58:59]
	v_rcp_f32_e32 v130, v96
	v_cndmask_b32_e64 v129, v126, 1.0, s[58:59]
	v_rcp_f32_e32 v131, v97
	v_rcp_f32_e32 v132, v98
	v_rcp_f32_e32 v133, v99
	v_cndmask_b32_e64 v124, v124, 1.0, s[58:59]
	v_cndmask_b32_e64 v125, v127, 1.0, s[58:59]
	v_pk_mul_f32 v[46:47], v[56:57], v[46:47]
	v_pk_mul_f32 v[2:3], v[2:3], v[44:45]
	v_pk_mul_f32 v[44:45], v[46:47], v[110:111]
	v_pk_mul_f32 v[56:57], v[2:3], v[108:109]
	v_pk_mul_f32 v[46:47], v[124:125], v[46:47]
	v_pk_mul_f32 v[2:3], v[128:129], v[2:3]
	v_pk_mul_f32 v[52:53], v[96:97], v[52:53]
	v_cvt_pk_bf16_f32 v2, v2, v3
	v_cvt_pk_bf16_f32 v3, v46, v47
	v_pk_mul_f32 v[46:47], v[98:99], v[54:55]
	v_cvt_pk_bf16_f32 v52, v52, v53
	v_cvt_pk_bf16_f32 v53, v46, v47
	v_add_u32_e32 v54, 8, v145
	ds_write2st64_b64 v54, v[2:3], v[52:53] offset0:104 offset1:122
	v_pk_mul_f32 v[2:3], v[132:133], v[44:45]
	v_pk_mul_f32 v[46:47], v[130:131], v[56:57]
	v_pk_mul_f32 v[52:53], v[130:131], v[106:107]
	v_cvt_pk_bf16_f32 v46, v46, v47
	v_cvt_pk_bf16_f32 v47, v2, v3
	v_pk_mul_f32 v[2:3], v[132:133], v[100:101]
	s_waitcnt lgkmcnt(3)
	v_pk_mul_f32 v[126:127], v[130:131], v[48:49]
	s_waitcnt lgkmcnt(1)
	v_pk_mul_f32 v[134:135], v[132:133], v[50:51]
	v_cvt_pk_bf16_f32 v52, v52, v53
	v_cvt_pk_bf16_f32 v53, v2, v3
	ds_write2st64_b64 v54, v[46:47], v[52:53] offset0:49 offset1:67
	v_pk_mul_f32 v[2:3], v[134:135], v[44:45]
	v_pk_mul_f32 v[44:45], v[126:127], v[56:57]
	v_pk_mul_f32 v[52:53], v[126:127], v[106:107]
	v_pk_mul_f32 v[46:47], v[134:135], v[100:101]
	v_cvt_pk_bf16_f32 v44, v44, v52
	v_cvt_pk_bf16_f32 v45, v45, v53
	v_add_u32_e32 v52, 0x1000, v195
	ds_write2_b32 v52, v44, v45 offset0:64 offset1:132
	v_cvt_pk_bf16_f32 v2, v2, v46
	v_cvt_pk_bf16_f32 v3, v3, v47
	v_add_u32_e32 v44, 0x1200, v195
	ds_write2_b32 v44, v2, v3 offset0:72 offset1:140
	s_and_saveexec_b64 s[22:23], s[60:61]
	ds_write_b128 v175, v[48:51] offset:64
	s_or_b64 exec, exec, s[22:23]
	s_and_saveexec_b64 s[22:23], s[72:73]
	s_cbranch_execz .LBB0_114
	v_mov_b32_e32 v1, v75
	s_nop 1
	v_permlane16_swap_b32_e32 v75, v1
	v_add_f32_e32 v1, v75, v1
	v_mov_b32_e32 v2, v1
	s_nop 1
	v_permlane32_swap_b32_e32 v1, v2
	s_and_b64 exec, exec, s[48:49]
	s_cbranch_execz .LBB0_114
	v_lshlrev_b64 v[44:45], 6, v[88:89]
	v_lshl_add_u64 v[44:45], v[82:83], 0, v[44:45]
	s_waitcnt lgkmcnt(0)
	v_add_f32_e32 v1, v1, v2
	global_store_dword v[44:45], v1, off

; #define LAS __attribute__((address_space(3)))
; __device__ __forceinline__ void rw_scan(LAS unsigned char* L, const bf16_t* Rg, const bf16_t* Kg, const bf16_t* Vg, const bf16_t* VF, const bf16_t* LO, const bf16_t* wlbT, const bf16_t* albT, const bf16_t* vlbT, ...
;     ...
;             if (m >= 2) {
;                 const LAS bf16_t* ob = OUTb + (m & 1) * (64 * 18);
;                 const int i = tid >> 3, rr = (tid & 7) * 2; const int st = 64 * (m - 2) + i, t = g ? (S_ - 1 - st) : st; const size_t row = (size_t)b * S_ + t;
;                 *(unsigned*)(WKV + ((size_t)g * T_ + row) * 1024 + h * 64 + 16 * q + rr) = *(const LAS unsigned*)(ob + i * 18 + rr);
.LBB0_121:
	s_or_b64 exec, exec, s[22:23]
	s_cmp_lg_u32 s81, 0
	s_cselect_b64 s[22:23], -1, 0
	s_cmp_eq_u32 s81, 0
	s_cbranch_scc1 .LBB0_123
	v_lshl_add_u32 v1, s81, 6, v142
	s_waitcnt lgkmcnt(0)
	v_sub_u32_e32 v2, 0x3fff, v1
	v_cndmask_b32_e64 v2, v2, v1, s[70:71]
	v_ashrrev_i32_e32 v3, 31, v2
	v_lshl_add_u64 v[2:3], v[2:3], 0, s[38:39]
	v_lshlrev_b64 v[2:3], 11, v[2:3]
	v_lshl_add_u64 v[2:3], v[84:85], 0, v[2:3]
	global_store_dword v[2:3], v250, off

; #define LAS __attribute__((address_space(3)))
; __device__ __forceinline__ f32x4 mma16(bf16x8 a, bf16x8 b, f32x4 c) { return __builtin_amdgcn_mfma_f32_16x16x32_bf16(a, b, c, 0, 0, 0); }
; __device__ __forceinline__ void rw_scan(LAS unsigned char* L, const bf16_t* Rg, const bf16_t* Kg, const bf16_t* Vg, const bf16_t* VF, const bf16_t* LO, const bf16_t* wlbT, const bf16_t* albT, const bf16_t* vlbT, ...
;     ...
;                 f32x4 accw[2], acca[2], accv = (f32x4){0.f, 0.f, 0.f, 0.f};
; #pragma unroll
;                 for (int tl = 0; tl < 2; ++tl) { const int td = 2 * half + tl; accw[tl] = (f32x4){0.f, 0.f, 0.f, 0.f}; acca[tl] = (f32x4){0.f, 0.f, 0.f, 0.f};
;                     accw[tl] = mma16(lfrag(BTw, 72, td * 16 + fr, 8 * fq), flw0, accw[tl]); accw[tl] = mma16(lfrag(BTw, 72, td * 16 + fr, 32 + 8 * fq), flw1, accw[tl]);
;                     acca[tl] = mma16(lfrag(BTa, 72, td * 16 + fr, 8 * fq), fla0, acca[tl]); acca[tl] = mma16(lfrag(BTa, 72, td * 16 + fr, 32 + 8 * fq), fla1, acca[tl]); }
;                 if (hasvf && hasv) accv = mma16(lfrag(BTv, 40, q * 16 + fr, 8 * fq), flv, accv);
;                 float n2 = 0.f;
; #pragma unroll
;                 for (int td = 0; td < 4; ++td) { const f32x4 kk_ = unpk4(xK[td]) * *(const LAS f32x4*)(CSTb + 192 + td * 16 + 4 * fq); n2 += (kk_[0] * kk_[0] + kk_[1] * kk_[1]) + (kk_[2] * kk_[2] + kk_[3] * kk_[3]); }
;                 n2 += __shfl_xor(n2, 16); n2 += __shfl_xor(n2, 32);
;                 const float inv = fminf(__builtin_amdgcn_rsqf(n2), 1e12f);
;                 const f32x4 krs0 = unpk4(half ? xK[2] : xK[0]), krs1 = unpk4(half ? xK[3] : xK[1]), r4s0 = unpk4(xR[0]), r4s1 = unpk4(xR[1]); const f32x4 v4u = unpk4(xV), vf4u = unpk4(xVF);
;                 asm volatile("" ::: "memory");
;                 if (m + 1 < 256) RW_LOADS(m + 1);
;     ...
;             if (m >= 2) {
;                 const LAS bf16_t* ob = OUTb + (m & 1) * (64 * 18);
;                 const int i = tid >> 3, rr = (tid & 7) * 2; const int st = 64 * (m - 2) + i, t = g ? (S_ - 1 - st) : st; const size_t row = (size_t)b * S_ + t;
;                 *(unsigned*)(WKV + ((size_t)g * T_ + row) * 1024 + h * 64 + 16 * q + rr) = *(const LAS unsigned*)(ob + i * 18 + rr);
.LBB0_151:
	s_or_b64 exec, exec, s[24:25]
	ds_read_b32 v250, v143 offset:50944
	s_and_b64 vcc, exec, s[74:75]
	s_cbranch_vccnz .LBB0_161
	v_add_u32_e32 v1, v66, v224
	ds_read_b128 v[212:215], v68
	ds_read_b128 v[216:219], v68 offset:64
	ds_read_b128 v[230:233], v68 offset:9216
	ds_read_b128 v[234:237], v68 offset:9280
	ds_read_b128 v[238:241], v68 offset:2304
	ds_read_b128 v[246:249], v68 offset:2368
	ds_read_b128 v[88:91], v68 offset:11520
	ds_read_b128 v[96:99], v68 offset:11584
	ds_read_b128 v[106:109], v66 offset:24320
	ds_read_b128 v[202:205], v66 offset:24384
	ds_read_b128 v[206:209], v66 offset:24448
	ds_read_b128 v[134:137], v66 offset:24512
	ds_read_b128 v[126:129], v69 offset:23552
	ds_read_b128 v[130:133], v69 offset:24064
	s_waitcnt vmcnt(9) lgkmcnt(13)
	v_mfma_f32_16x16x32_bf16 v[40:43], v[212:215], v[20:23], 0
	ds_read_b128 v[212:215], v1 offset:18432
	s_waitcnt vmcnt(8) lgkmcnt(13)
	v_mfma_f32_16x16x32_bf16 v[56:59], v[216:219], v[16:19], v[40:43]
	s_waitcnt vmcnt(7) lgkmcnt(12)
	v_mfma_f32_16x16x32_bf16 v[40:43], v[230:233], v[12:15], 0
	s_waitcnt vmcnt(6) lgkmcnt(11)
	v_mfma_f32_16x16x32_bf16 v[52:55], v[234:237], v[8:11], v[40:43]
	s_waitcnt lgkmcnt(10)
	v_mfma_f32_16x16x32_bf16 v[40:43], v[238:241], v[20:23], 0
	s_waitcnt lgkmcnt(9)
	v_mfma_f32_16x16x32_bf16 v[48:51], v[246:249], v[16:19], v[40:43]
	s_waitcnt lgkmcnt(8)
	v_mfma_f32_16x16x32_bf16 v[40:43], v[88:91], v[12:15], 0
	s_waitcnt lgkmcnt(7)
	v_mfma_f32_16x16x32_bf16 v[44:47], v[96:99], v[8:11], v[40:43]
	ds_read_b128 v[216:219], v69 offset:24320
	ds_read_b128 v[230:233], v69 offset:24576
	ds_read_b128 v[234:237], v69 offset:24832
	ds_read_b128 v[238:241], v69 offset:23616
	ds_read_b128 v[246:249], v69 offset:24128
	s_nop 6
	v_mov_b32_e32 v40, 0
	v_mov_b32_e32 v41, 0
	v_mov_b32_e32 v42, 0
	v_mov_b32_e32 v43, 0
	s_and_saveexec_b64 s[24:25], s[40:41]
	s_cbranch_execz .LBB0_154
	s_waitcnt lgkmcnt(5)
	v_mfma_f32_16x16x32_bf16 v[40:43], v[212:215], v[4:7], 0
.LBB0_154:
	s_or_b64 exec, exec, s[24:25]
	ds_read_b128 v[212:215], v69 offset:24384
	s_waitcnt vmcnt(5)
	v_lshlrev_b32_e32 v2, 16, v120
	v_and_b32_e32 v3, 0xffff0000, v120
	v_lshlrev_b32_e32 v92, 16, v121
	v_and_b32_e32 v93, 0xffff0000, v121
	s_waitcnt lgkmcnt(6)
	v_pk_mul_f32 v[2:3], v[106:107], v[2:3]
	v_pk_mul_f32 v[90:91], v[108:109], v[92:93]
	v_mul_f32_e32 v1, v3, v3
	v_fmac_f32_e32 v1, v2, v2
	v_mul_f32_e32 v2, v91, v91
	v_fmac_f32_e32 v2, v90, v90
	v_add_f32_e32 v1, v1, v2
	s_waitcnt vmcnt(4)
	v_lshlrev_b32_e32 v2, 16, v114
	v_and_b32_e32 v3, 0xffff0000, v114
	v_lshlrev_b32_e32 v92, 16, v115
	v_and_b32_e32 v93, 0xffff0000, v115
	s_nop 0
	v_pk_mul_f32 v[2:3], v[202:203], v[2:3]
	v_pk_mul_f32 v[90:91], v[204:205], v[92:93]
	v_mul_f32_e32 v3, v3, v3
	v_fmac_f32_e32 v3, v2, v2
	v_mul_f32_e32 v2, v91, v91
	v_fmac_f32_e32 v2, v90, v90
	v_add_f32_e32 v2, v3, v2
	v_add_f32_e32 v1, v1, v2
	s_waitcnt vmcnt(3)
	v_lshlrev_b32_e32 v2, 16, v122
	v_and_b32_e32 v3, 0xffff0000, v122
	v_lshlrev_b32_e32 v92, 16, v123
	v_and_b32_e32 v93, 0xffff0000, v123
	s_nop 0
	v_pk_mul_f32 v[2:3], v[206:207], v[2:3]
	v_pk_mul_f32 v[90:91], v[208:209], v[92:93]
	v_mul_f32_e32 v3, v3, v3
	v_fmac_f32_e32 v3, v2, v2
	v_mul_f32_e32 v2, v91, v91
	v_fmac_f32_e32 v2, v90, v90
	v_add_f32_e32 v2, v3, v2
	v_add_f32_e32 v1, v1, v2
	s_waitcnt vmcnt(2)
	v_lshlrev_b32_e32 v2, 16, v116
	v_and_b32_e32 v3, 0xffff0000, v116
	v_lshlrev_b32_e32 v92, 16, v117
	v_and_b32_e32 v93, 0xffff0000, v117
	s_nop 0
	v_pk_mul_f32 v[2:3], v[134:135], v[2:3]
	v_pk_mul_f32 v[90:91], v[136:137], v[92:93]
	v_mul_f32_e32 v3, v3, v3
	v_fmac_f32_e32 v3, v2, v2
	v_mul_f32_e32 v2, v91, v91
	v_fmac_f32_e32 v2, v90, v90
	v_add_f32_e32 v2, v3, v2
	v_and_b32_e32 v3, 64, v200
	v_add_f32_e32 v2, v1, v2
	v_xor_b32_e32 v1, 16, v200
	v_add_u32_e32 v3, 64, v3
	v_cmp_lt_i32_e32 vcc, v1, v3
	s_cmpk_eq_i32 s81, 0xfe
	s_nop 0
	v_cndmask_b32_e32 v1, v200, v1, vcc
	v_lshlrev_b32_e32 v1, 2, v1
	v_mov_b32_e32 v73, v2
	s_nop 1
	v_permlane16_swap_b32_e32 v2, v73
	v_add_f32_e32 v225, v2, v73
	v_xor_b32_e32 v2, 32, v200
	v_cmp_lt_i32_e32 vcc, v2, v3
	s_nop 1
	v_cndmask_b32_e32 v2, v200, v2, vcc
	v_lshlrev_b32_e32 v73, 2, v2
	v_mov_b32_e32 v226, v225
	s_nop 1
	v_permlane32_swap_b32_e32 v225, v226
	s_cbranch_scc1 .LBB0_162
	v_lshl_add_u32 v2, s26, 6, v141
	v_sub_u32_e32 v3, 0x3fff, v2
	v_cndmask_b32_e64 v2, v3, v2, s[70:71]
	v_add_u32_e32 v88, s38, v2
	v_mov_b32_e32 v89, v0
	v_readlane_b32 s2, v251, 34
	v_lshlrev_b64 v[2:3], 10, v[88:89]
	v_readlane_b32 s3, v251, 35
	v_mov_b32_e32 v75, v0
	s_nop 0
	v_lshl_add_u64 v[90:91], s[2:3], 0, v[2:3]
	v_lshl_add_u64 v[8:9], s[20:21], 1, v[90:91]
	v_lshl_add_u64 v[8:9], v[8:9], 0, v[74:75]
	global_load_dwordx4 v[20:23], v[8:9], off
	global_load_dwordx4 v[16:19], v[8:9], off offset:64
	global_load_dwordx4 v[12:15], v[8:9], off offset:256
	s_nop 0
	global_load_dwordx4 v[8:11], v[8:9], off offset:320
	s_and_saveexec_b64 s[24:25], s[40:41]
	s_cbranch_execz .LBB0_157
	v_lshl_add_u64 v[4:5], v[90:91], 0, v[74:75]
	global_load_dwordx4 v[4:7], v[4:5], off offset:832

; #define LAS __attribute__((address_space(3)))
; __device__ __forceinline__ f32x4 sigm4(f32x4 x) { return (f32x4){sigm(x[0]), sigm(x[1]), sigm(x[2]), sigm(x[3])}; }
; template <int CTRL> __device__ __forceinline__ float dpp0(float x) { return __builtin_bit_cast(float, __builtin_amdgcn_update_dpp(0, __builtin_bit_cast(int, x), CTRL, 0xf, 0xf, true)); }
; __device__ __forceinline__ float row16_scan(float x) { x += dpp0<0x111>(x); x += dpp0<0x112>(x); x += dpp0<0x114>(x); x += dpp0<0x118>(x); return x; }
; __device__ __forceinline__ void rw_scan(LAS unsigned char* L, const bf16_t* Rg, const bf16_t* Kg, const bf16_t* Vg, const bf16_t* VF, const bf16_t* LO, const bf16_t* wlbT, const bf16_t* albT, const bf16_t* vlbT, ...
;     ...
;                 float bs = 0.f;
; #pragma unroll
;                 for (int tl = 0; tl < 2; ++tl) { const int td = 2 * half + tl; const int c4 = td * 16 + 4 * fq;
;                     const f32x4 lw = sigm4(*(const LAS f32x4*)(CSTb + c4) + accw[tl]) * (-0.6065306597126334f * 1.4426950408889634f);
;                     f32x4 cl;
; #pragma unroll
;                     for (int r = 0; r < 4; ++r) cl[r] = row16_scan(lw[r]);
;                     const f32x4 ep = (f32x4){__builtin_amdgcn_exp2f(cl[0]), __builtin_amdgcn_exp2f(cl[1]), __builtin_amdgcn_exp2f(cl[2]), __builtin_amdgcn_exp2f(cl[3])};
;                     f32x4 epL, em, en;
; #pragma unroll
;                     for (int r = 0; r < 4; ++r) { epL[r] = __shfl(ep[r], (lane & 48) | 15); const float sh = dpp0<0x111>(ep[r]); em[r] = (fr == 0) ? 1.f : sh; en[r] = __builtin_amdgcn_rcpf(ep[r]); }
;                     const f32x4 eL = epL * en;
;                     const f32x4 a4 = sigm4(*(const LAS f32x4*)(CSTb + 128 + c4) + acca[tl]);
;                     const f32x4 kr = tl ? krs1 : krs0; const f32x4 kk4 = kr * *(const LAS f32x4*)(CSTb + 192 + c4) * inv;
;                     const f32x4 kd4 = kr * (1.f + (a4 - 1.f) * *(const LAS f32x4*)(CSTb + 256 + c4)); const f32x4 b4 = kk4 * a4; const f32x4 r4 = tl ? r4s1 : r4s0;
;                     if (ti == q) { const f32x4 rk = r4 * kd4 * *(const LAS f32x4*)(CSTb + 320 + c4); bs += (rk[0] + rk[1]) + (rk[2] + rk[3]); }
.LBB0_163:
	v_cndmask_b32_e64 v2, v123, v121, s[46:47]
	v_cndmask_b32_e64 v3, v122, v120, s[46:47]
	v_lshlrev_b32_e32 v124, 16, v2
	v_and_b32_e32 v125, 0xffff0000, v2
	v_and_or_b32 v2, v200, 64, v64
	s_waitcnt lgkmcnt(1)
	v_pk_add_f32 v[56:57], v[56:57], v[126:127]
	v_lshlrev_b32_e32 v122, 16, v3
	v_and_b32_e32 v123, 0xffff0000, v3
	v_lshl_or_b32 v3, v2, 2, 60
	v_mul_f32_e32 v2, 0xbfb8aa3b, v56
	v_exp_f32_e32 v2, v2
	v_mul_f32_e32 v56, 0xbfb8aa3b, v57
	v_exp_f32_e32 v75, v56
	v_pk_add_f32 v[56:57], v[58:59], v[128:129]
	v_add_f32_e32 v2, 1.0, v2
	v_rcp_f32_e32 v2, v2
	v_mul_f32_e32 v56, 0xbfb8aa3b, v56
	v_exp_f32_e32 v56, v56
	v_add_f32_e32 v58, 1.0, v75
	v_mul_f32_e32 v57, 0xbfb8aa3b, v57
	v_rcp_f32_e32 v58, v58
	v_exp_f32_e32 v57, v57
	v_mul_f32_e32 v59, 0xbf60028a, v2
	v_add_f32_e32 v56, 1.0, v56
	v_rcp_f32_e32 v56, v56
	v_mov_b32_dpp v59, v59 row_shr:1 row_mask:0xf bank_mask:0xf bound_ctrl:1
	v_fmac_f32_e32 v59, 0xbf60028a, v2
	v_add_f32_e32 v57, 1.0, v57
	v_rcp_f32_e32 v57, v57
	v_add_f32_dpp v2, v59, v59 row_shr:2 row_mask:0xf bank_mask:0xf bound_ctrl:1
	v_mul_f32_e32 v59, 0xbf60028a, v58
	s_waitcnt lgkmcnt(0)
	v_pk_add_f32 v[52:53], v[52:53], v[130:131]
	v_add_f32_dpp v2, v2, v2 row_shr:4 row_mask:0xf bank_mask:0xf bound_ctrl:1
	v_mov_b32_dpp v59, v59 row_shr:1 row_mask:0xf bank_mask:0xf bound_ctrl:1
	v_fmac_f32_e32 v59, 0xbf60028a, v58
	v_mul_f32_e32 v52, 0xbfb8aa3b, v52
	v_add_f32_dpp v2, v2, v2 row_shr:8 row_mask:0xf bank_mask:0xf bound_ctrl:1
	v_add_f32_dpp v58, v59, v59 row_shr:2 row_mask:0xf bank_mask:0xf bound_ctrl:1
	v_mul_f32_e32 v59, 0xbf60028a, v56
	v_exp_f32_e32 v126, v2
	v_add_f32_dpp v58, v58, v58 row_shr:4 row_mask:0xf bank_mask:0xf bound_ctrl:1
	v_mov_b32_dpp v59, v59 row_shr:1 row_mask:0xf bank_mask:0xf bound_ctrl:1
	v_fmac_f32_e32 v59, 0xbf60028a, v56
	v_add_f32_dpp v58, v58, v58 row_shr:8 row_mask:0xf bank_mask:0xf bound_ctrl:1
	v_exp_f32_e32 v127, v58
	v_add_f32_dpp v56, v59, v59 row_shr:2 row_mask:0xf bank_mask:0xf bound_ctrl:1
	v_mul_f32_e32 v59, 0xbf60028a, v57
	v_lshlrev_b32_e32 v120, 16, v118
	v_add_f32_dpp v56, v56, v56 row_shr:4 row_mask:0xf bank_mask:0xf bound_ctrl:1
	v_mov_b32_dpp v59, v59 row_shr:1 row_mask:0xf bank_mask:0xf bound_ctrl:1
	v_fmac_f32_e32 v59, 0xbf60028a, v57
	v_add_f32_dpp v56, v56, v56 row_shr:8 row_mask:0xf bank_mask:0xf bound_ctrl:1
	v_exp_f32_e32 v128, v56
	v_add_f32_dpp v57, v59, v59 row_shr:2 row_mask:0xf bank_mask:0xf bound_ctrl:1
	v_exp_f32_e32 v59, v52
	v_mul_f32_e32 v52, 0xbfb8aa3b, v53
	v_exp_f32_e32 v75, v52
	v_pk_add_f32 v[52:53], v[54:55], v[132:133]
	v_add_f32_dpp v57, v57, v57 row_shr:4 row_mask:0xf bank_mask:0xf bound_ctrl:1
	v_mul_f32_e32 v52, 0xbfb8aa3b, v52
	v_exp_f32_e32 v52, v52
	v_mul_f32_e32 v53, 0xbfb8aa3b, v53
	v_exp_f32_e32 v53, v53
	v_add_f32_dpp v57, v57, v57 row_shr:8 row_mask:0xf bank_mask:0xf bound_ctrl:1
	v_exp_f32_e32 v129, v57
	v_add_f32_e32 v54, 1.0, v59
	v_add_f32_e32 v52, 1.0, v52
	v_rcp_f32_e32 v134, v54
	v_add_f32_e32 v54, 1.0, v75
	v_rcp_f32_e32 v136, v52
	v_add_f32_e32 v52, 1.0, v53
	v_rcp_f32_e32 v135, v54
	v_rcp_f32_e32 v137, v52
	ds_bpermute_b32 v56, v3, v126
	ds_bpermute_b32 v57, v3, v127
	ds_bpermute_b32 v58, v3, v128
	ds_bpermute_b32 v59, v3, v129
	v_pk_add_f32 v[198:199], v[136:137], -1.0 op_sel_hi:[1,0]
	v_pk_add_f32 v[202:203], v[134:135], -1.0 op_sel_hi:[1,0]
	s_waitcnt lgkmcnt(4)
	v_pk_fma_f32 v[132:133], v[232:233], v[198:199], 1.0 op_sel_hi:[1,1,0]
	v_pk_fma_f32 v[198:199], v[230:231], v[202:203], 1.0 op_sel_hi:[1,1,0]
	v_and_b32_e32 v121, 0xffff0000, v118
	v_lshlrev_b32_e32 v118, 16, v119
	v_and_b32_e32 v119, 0xffff0000, v119
	v_mov_b32_dpp v2, v126 row_shr:1 row_mask:0xf bank_mask:0xf bound_ctrl:1
	v_mov_b32_dpp v228, v127 row_shr:1 row_mask:0xf bank_mask:0xf bound_ctrl:1
	v_mov_b32_dpp v227, v128 row_shr:1 row_mask:0xf bank_mask:0xf bound_ctrl:1
	v_mov_b32_dpp v229, v129 row_shr:1 row_mask:0xf bank_mask:0xf bound_ctrl:1
	v_pk_mul_f32 v[130:131], v[132:133], v[124:125]
	v_pk_mul_f32 v[132:133], v[198:199], v[122:123]
	v_mov_b32_e32 v75, 0
	s_and_saveexec_b64 s[24:25], s[72:73]
	s_cbranch_execz .LBB0_165
	v_pk_mul_f32 v[198:199], v[130:131], v[118:119]
	v_pk_mul_f32 v[202:203], v[132:133], v[120:121]
	v_pk_mul_f32 v[198:199], v[198:199], v[236:237]
	v_pk_mul_f32 v[202:203], v[202:203], v[234:235]
	s_nop 0
	v_pk_mov_b32 v[204:205], v[202:203], v[198:199] op_sel:[1,0]
	v_mov_b32_e32 v203, v199
	v_pk_add_f32 v[198:199], v[204:205], v[202:203]
	s_nop 0
	v_add_f32_e32 v75, v198, v199
	v_add_f32_e32 v75, 0, v75
; #define LAS __attribute__((address_space(3)))
; __device__ __forceinline__ void rw_scan(LAS unsigned char* L, const bf16_t* Rg, const bf16_t* Kg, const bf16_t* Vg, const bf16_t* VF, const bf16_t* LO, const bf16_t* wlbT, const bf16_t* albT, const bf16_t* vlbT, ...
;     ...
;                 for (int tl = 0; tl < 2; ++tl) { const int td = 2 * half + tl; const int c4 = td * 16 + 4 * fq;
;                     const f32x4 lw = sigm4(*(const LAS f32x4*)(CSTb + c4) + accw[tl]) * (-0.6065306597126334f * 1.4426950408889634f);
;                     f32x4 cl;
; #pragma unroll
;                     for (int r = 0; r < 4; ++r) cl[r] = row16_scan(lw[r]);
;                     const f32x4 ep = (f32x4){__builtin_amdgcn_exp2f(cl[0]), __builtin_amdgcn_exp2f(cl[1]), __builtin_amdgcn_exp2f(cl[2]), __builtin_amdgcn_exp2f(cl[3])};
;                     f32x4 epL, em, en;
; #pragma unroll
;                     for (int r = 0; r < 4; ++r) { epL[r] = __shfl(ep[r], (lane & 48) | 15); const float sh = dpp0<0x111>(ep[r]); em[r] = (fr == 0) ? 1.f : sh; en[r] = __builtin_amdgcn_rcpf(ep[r]); }
;                     const f32x4 eL = epL * en;
;                     const f32x4 a4 = sigm4(*(const LAS f32x4*)(CSTb + 128 + c4) + acca[tl]);
;                     const f32x4 kr = tl ? krs1 : krs0; const f32x4 kk4 = kr * *(const LAS f32x4*)(CSTb + 192 + c4) * inv;
;                     const f32x4 kd4 = kr * (1.f + (a4 - 1.f) * *(const LAS f32x4*)(CSTb + 256 + c4)); const f32x4 b4 = kk4 * a4; const f32x4 r4 = tl ? r4s1 : r4s0;
;                     if (ti == q) { const f32x4 rk = r4 * kd4 * *(const LAS f32x4*)(CSTb + 320 + c4); bs += (rk[0] + rk[1]) + (rk[2] + rk[3]); }
;                     const int p4 = 32 * (td >> 1) + 8 * fq + 4 * (td & 1);
;                     *(LAS u32x2*)(KQ + irow * 72 + p4) = pk4(kk4 * em); *(LAS u32x2*)(RQ + irow * 72 + p4) = pk4(r4 * ep);
;                     *(LAS u32x2*)(BD + irow * 72 + p4) = pk4(b4 * en); *(LAS u32x2*)(KD + irow * 72 + p4) = pk4(kd4 * en);
;                     const f32x4 bl = b4 * eL, kl = kd4 * eL;
; #pragma unroll
;                     for (int r = 0; r < 4; ++r) *(LAS unsigned*)(W2 + (c4 + r) * 136 + ti * 32 + 8 * (fr >> 2) + 2 * (fr & 3)) = cvt_pk_bf16(bl[r], kl[r]);
;                     if (fr == 15) *(LAS f32x4*)(LLs + ti * 64 + c4) = epL;
.LBB0_165:
	s_or_b64 exec, exec, s[24:25]
	v_add_f32_e32 v198, v225, v226
	v_rsq_f32_e32 v203, v198
	v_cndmask_b32_e64 v198, v2, 1.0, s[58:59]
	v_pk_mul_f32 v[54:55], v[218:219], v[124:125]
	v_pk_mul_f32 v[52:53], v[216:217], v[122:123]
	v_min_f32_e32 v2, 0x5368d4a5, v203
	v_cndmask_b32_e64 v199, v228, 1.0, s[58:59]
	v_cndmask_b32_e64 v206, v227, 1.0, s[58:59]
	v_cndmask_b32_e64 v207, v229, 1.0, s[58:59]
	v_pk_mul_f32 v[54:55], v[2:3], v[54:55] op_sel_hi:[0,1]
	v_pk_mul_f32 v[52:53], v[2:3], v[52:53] op_sel_hi:[0,1]
	v_rcp_f32_e32 v202, v126
	v_rcp_f32_e32 v203, v127
	v_rcp_f32_e32 v204, v128
	v_rcp_f32_e32 v205, v129
	v_pk_mul_f32 v[122:123], v[52:53], v[134:135]
	v_pk_mul_f32 v[124:125], v[54:55], v[136:137]
	v_pk_mul_f32 v[54:55], v[206:207], v[54:55]
	v_pk_mul_f32 v[52:53], v[198:199], v[52:53]
	s_waitcnt lgkmcnt(2)
	v_pk_mul_f32 v[208:209], v[202:203], v[56:57]
	v_cvt_pk_bf16_f32 v52, v52, v53
	v_cvt_pk_bf16_f32 v53, v54, v55
	ds_write_b64 v179, v[52:53]
	v_pk_mul_f32 v[52:53], v[128:129], v[118:119]
	v_pk_mul_f32 v[54:55], v[126:127], v[120:121]
	v_pk_mul_f32 v[118:119], v[202:203], v[132:133]
	v_cvt_pk_bf16_f32 v54, v54, v55
	v_cvt_pk_bf16_f32 v55, v52, v53
	ds_write_b64 v180, v[54:55]
	v_pk_mul_f32 v[52:53], v[204:205], v[124:125]
	v_pk_mul_f32 v[54:55], v[202:203], v[122:123]
	s_waitcnt lgkmcnt(2)
	v_pk_mul_f32 v[210:211], v[204:205], v[58:59]
	v_cvt_pk_bf16_f32 v54, v54, v55
	v_cvt_pk_bf16_f32 v55, v52, v53
	v_pk_mul_f32 v[52:53], v[204:205], v[130:131]
	v_cvt_pk_bf16_f32 v118, v118, v119
	v_cvt_pk_bf16_f32 v119, v52, v53
	ds_write2st64_b64 v145, v[54:55], v[118:119] offset0:49 offset1:67
	v_pk_mul_f32 v[52:53], v[210:211], v[124:125]
	v_pk_mul_f32 v[54:55], v[208:209], v[122:123]
	v_pk_mul_f32 v[118:119], v[210:211], v[130:131]
	v_pk_mul_f32 v[120:121], v[208:209], v[132:133]
	v_cvt_pk_bf16_f32 v52, v52, v118
	v_cvt_pk_bf16_f32 v54, v54, v120
	v_cvt_pk_bf16_f32 v55, v55, v121
	v_cvt_pk_bf16_f32 v53, v53, v119
	ds_write2_b32 v223, v54, v55 offset1:68
	ds_write2_b32 v223, v52, v53 offset0:136 offset1:204
	s_and_saveexec_b64 s[24:25], s[60:61]
	ds_write_b128 v181, v[56:59]
	s_or_b64 exec, exec, s[24:25]
	v_cndmask_b32_e64 v52, v117, v115, s[46:47]
	v_cndmask_b32_e64 v53, v116, v114, s[46:47]
	ds_read_b128 v[216:219], v69 offset:24640
	ds_read_b128 v[230:233], v69 offset:24896
	v_lshlrev_b32_e32 v56, 16, v53
	v_and_b32_e32 v57, 0xffff0000, v53
	v_lshlrev_b32_e32 v58, 16, v52
	v_pk_add_f32 v[48:49], v[48:49], v[238:239]
	v_and_b32_e32 v59, 0xffff0000, v52
	v_mul_f32_e32 v48, 0xbfb8aa3b, v48
	v_lshlrev_b32_e32 v52, 16, v112
	v_and_b32_e32 v53, 0xffff0000, v112
	v_exp_f32_e32 v112, v48
	v_mul_f32_e32 v48, 0xbfb8aa3b, v49
	v_lshlrev_b32_e32 v54, 16, v113
	v_and_b32_e32 v55, 0xffff0000, v113
	v_exp_f32_e32 v113, v48
	v_pk_add_f32 v[48:49], v[50:51], v[240:241]
	v_add_f32_e32 v50, 1.0, v112
	v_rcp_f32_e32 v50, v50
	v_mul_f32_e32 v48, 0xbfb8aa3b, v48
	v_add_f32_e32 v51, 1.0, v113
	v_exp_f32_e32 v48, v48
	v_rcp_f32_e32 v51, v51
	v_mul_f32_e32 v49, 0xbfb8aa3b, v49
	v_mul_f32_e32 v112, 0xbf60028a, v50
	v_exp_f32_e32 v49, v49
	v_add_f32_e32 v48, 1.0, v48
	v_mov_b32_dpp v112, v112 row_shr:1 row_mask:0xf bank_mask:0xf bound_ctrl:1
	v_fmac_f32_e32 v112, 0xbf60028a, v50
	v_rcp_f32_e32 v48, v48
	v_add_f32_e32 v49, 1.0, v49
	v_add_f32_dpp v50, v112, v112 row_shr:2 row_mask:0xf bank_mask:0xf bound_ctrl:1
	v_mul_f32_e32 v112, 0xbf60028a, v51
	v_rcp_f32_e32 v49, v49
	v_pk_add_f32 v[44:45], v[44:45], v[246:247]
	v_mov_b32_dpp v112, v112 row_shr:1 row_mask:0xf bank_mask:0xf bound_ctrl:1
	v_fmac_f32_e32 v112, 0xbf60028a, v51
	v_mul_f32_e32 v44, 0xbfb8aa3b, v44
	v_add_f32_dpp v50, v50, v50 row_shr:4 row_mask:0xf bank_mask:0xf bound_ctrl:1
	v_add_f32_dpp v51, v112, v112 row_shr:2 row_mask:0xf bank_mask:0xf bound_ctrl:1
	v_mul_f32_e32 v112, 0xbf60028a, v48
	v_add_f32_dpp v50, v50, v50 row_shr:8 row_mask:0xf bank_mask:0xf bound_ctrl:1
	v_add_f32_dpp v51, v51, v51 row_shr:4 row_mask:0xf bank_mask:0xf bound_ctrl:1
	v_mov_b32_dpp v112, v112 row_shr:1 row_mask:0xf bank_mask:0xf bound_ctrl:1
	v_fmac_f32_e32 v112, 0xbf60028a, v48
	v_add_f32_dpp v51, v51, v51 row_shr:8 row_mask:0xf bank_mask:0xf bound_ctrl:1
	v_exp_f32_e32 v113, v51
	v_exp_f32_e32 v51, v44
	v_mul_f32_e32 v44, 0xbfb8aa3b, v45
	v_add_f32_dpp v48, v112, v112 row_shr:2 row_mask:0xf bank_mask:0xf bound_ctrl:1
	v_mul_f32_e32 v112, 0xbf60028a, v49
	v_exp_f32_e32 v116, v44
	v_pk_add_f32 v[44:45], v[46:47], v[248:249]
	v_mov_b32_dpp v112, v112 row_shr:1 row_mask:0xf bank_mask:0xf bound_ctrl:1
	v_mul_f32_e32 v44, 0xbfb8aa3b, v44
	v_fmac_f32_e32 v112, 0xbf60028a, v49
	v_exp_f32_e32 v44, v44
	v_mul_f32_e32 v45, 0xbfb8aa3b, v45
	v_add_f32_dpp v49, v112, v112 row_shr:2 row_mask:0xf bank_mask:0xf bound_ctrl:1
	v_exp_f32_e32 v45, v45
	v_add_f32_dpp v48, v48, v48 row_shr:4 row_mask:0xf bank_mask:0xf bound_ctrl:1
	v_add_f32_dpp v49, v49, v49 row_shr:4 row_mask:0xf bank_mask:0xf bound_ctrl:1
	v_exp_f32_e32 v112, v50
	v_add_f32_dpp v48, v48, v48 row_shr:8 row_mask:0xf bank_mask:0xf bound_ctrl:1
	v_add_f32_dpp v49, v49, v49 row_shr:8 row_mask:0xf bank_mask:0xf bound_ctrl:1
	v_exp_f32_e32 v114, v48
	v_exp_f32_e32 v115, v49
	v_add_f32_e32 v46, 1.0, v51
	v_add_f32_e32 v44, 1.0, v44
	v_rcp_f32_e32 v120, v46
	v_add_f32_e32 v46, 1.0, v116
	v_rcp_f32_e32 v122, v44
	v_add_f32_e32 v44, 1.0, v45
	v_rcp_f32_e32 v121, v46
	v_rcp_f32_e32 v123, v44
	ds_bpermute_b32 v48, v3, v112
	ds_bpermute_b32 v49, v3, v113
	ds_bpermute_b32 v50, v3, v114
	ds_bpermute_b32 v51, v3, v115
	v_pk_add_f32 v[128:129], v[122:123], -1.0 op_sel_hi:[1,0]
	v_pk_add_f32 v[130:131], v[120:121], -1.0 op_sel_hi:[1,0]
	s_waitcnt lgkmcnt(4)
	v_pk_fma_f32 v[118:119], v[218:219], v[128:129], 1.0 op_sel_hi:[1,1,0]
	v_pk_fma_f32 v[128:129], v[216:217], v[130:131], 1.0 op_sel_hi:[1,1,0]
	v_mov_b32_dpp v125, v112 row_shr:1 row_mask:0xf bank_mask:0xf bound_ctrl:1
	v_mov_b32_dpp v126, v113 row_shr:1 row_mask:0xf bank_mask:0xf bound_ctrl:1
	v_mov_b32_dpp v124, v114 row_shr:1 row_mask:0xf bank_mask:0xf bound_ctrl:1
	v_mov_b32_dpp v127, v115 row_shr:1 row_mask:0xf bank_mask:0xf bound_ctrl:1
	v_pk_mul_f32 v[116:117], v[118:119], v[58:59]
	v_pk_mul_f32 v[118:119], v[128:129], v[56:57]
	s_and_saveexec_b64 s[24:25], s[72:73]
	s_cbranch_execz .LBB0_169
	v_pk_mul_f32 v[132:133], v[116:117], v[54:55]
	v_pk_mul_f32 v[134:135], v[118:119], v[52:53]
	v_pk_mul_f32 v[130:131], v[132:133], v[232:233]
	v_pk_mul_f32 v[128:129], v[134:135], v[230:231]
	s_nop 0
	v_pk_mov_b32 v[132:133], v[128:129], v[130:131] op_sel:[1,0]
	v_mov_b32_e32 v129, v131
	v_pk_add_f32 v[128:129], v[132:133], v[128:129]
	s_nop 0
	v_add_f32_e32 v3, v128, v129
	v_add_f32_e32 v75, v75, v3
; #define LAS __attribute__((address_space(3)))
; __device__ __forceinline__ unsigned cvt_pk_bf16(float lo, float hi) { const f32x2_t v = {lo, hi}; const bf16x2_t b = __builtin_convertvector(v, bf16x2_t); return __builtin_bit_cast(unsigned, b); }
; __device__ __forceinline__ u32x2 pk4(f32x4 x) { u32x2 w; w.x = cvt_pk_bf16(x[0], x[1]); w.y = cvt_pk_bf16(x[2], x[3]); return w; }
; __device__ __forceinline__ void rw_scan(LAS unsigned char* L, const bf16_t* Rg, const bf16_t* Kg, const bf16_t* Vg, const bf16_t* VF, const bf16_t* LO, const bf16_t* wlbT, const bf16_t* albT, const bf16_t* vlbT, ...
;     ...
;                     const f32x4 kr = tl ? krs1 : krs0; const f32x4 kk4 = kr * *(const LAS f32x4*)(CSTb + 192 + c4) * inv;
;                     const f32x4 kd4 = kr * (1.f + (a4 - 1.f) * *(const LAS f32x4*)(CSTb + 256 + c4)); const f32x4 b4 = kk4 * a4; const f32x4 r4 = tl ? r4s1 : r4s0;
;                     if (ti == q) { const f32x4 rk = r4 * kd4 * *(const LAS f32x4*)(CSTb + 320 + c4); bs += (rk[0] + rk[1]) + (rk[2] + rk[3]); }
;                     const int p4 = 32 * (td >> 1) + 8 * fq + 4 * (td & 1);
;                     *(LAS u32x2*)(KQ + irow * 72 + p4) = pk4(kk4 * em); *(LAS u32x2*)(RQ + irow * 72 + p4) = pk4(r4 * ep);
;                     *(LAS u32x2*)(BD + irow * 72 + p4) = pk4(b4 * en); *(LAS u32x2*)(KD + irow * 72 + p4) = pk4(kd4 * en);
;                     const f32x4 bl = b4 * eL, kl = kd4 * eL;
; #pragma unroll
;                     for (int r = 0; r < 4; ++r) *(LAS unsigned*)(W2 + (c4 + r) * 136 + ti * 32 + 8 * (fr >> 2) + 2 * (fr & 3)) = cvt_pk_bf16(bl[r], kl[r]);
;                     if (fr == 15) *(LAS f32x4*)(LLs + ti * 64 + c4) = epL;
;                 }
;                 if (ti == q) { bs += __shfl_xor(bs, 16); bs += __shfl_xor(bs, 32);
;                     if (fq == 0) BON2[((size_t)(g * 2 + half) * T_ + rowcur) * 16 + h] = bs; }
.LBB0_169:
	s_or_b64 exec, exec, s[24:25]
	v_mov_b32_e32 v3, v2
	v_pk_mul_f32 v[46:47], v[214:215], v[58:59]
	v_pk_mul_f32 v[44:45], v[212:213], v[56:57]
	v_mov_b32_e32 v56, v2
	v_mov_b32_e32 v57, v2
	v_cndmask_b32_e64 v128, v125, 1.0, s[58:59]
	v_cndmask_b32_e64 v129, v126, 1.0, s[58:59]
	v_cndmask_b32_e64 v124, v124, 1.0, s[58:59]
	v_cndmask_b32_e64 v125, v127, 1.0, s[58:59]
	v_pk_mul_f32 v[46:47], v[56:57], v[46:47]
	v_pk_mul_f32 v[2:3], v[2:3], v[44:45]
	v_rcp_f32_e32 v130, v112
	v_rcp_f32_e32 v131, v113
	v_rcp_f32_e32 v132, v114
	v_rcp_f32_e32 v133, v115
	v_pk_mul_f32 v[44:45], v[46:47], v[122:123]
	v_pk_mul_f32 v[56:57], v[2:3], v[120:121]
	v_pk_mul_f32 v[46:47], v[124:125], v[46:47]
	v_pk_mul_f32 v[2:3], v[128:129], v[2:3]
	s_waitcnt lgkmcnt(2)
	v_pk_mul_f32 v[126:127], v[130:131], v[48:49]
	v_cvt_pk_bf16_f32 v2, v2, v3
	v_cvt_pk_bf16_f32 v3, v46, v47
	ds_write_b64 v179, v[2:3] offset:8
	v_pk_mul_f32 v[2:3], v[114:115], v[54:55]
	v_pk_mul_f32 v[46:47], v[112:113], v[52:53]
	v_pk_mul_f32 v[52:53], v[130:131], v[118:119]
	v_cvt_pk_bf16_f32 v46, v46, v47
	v_cvt_pk_bf16_f32 v47, v2, v3
	ds_write_b64 v180, v[46:47] offset:8
	v_pk_mul_f32 v[2:3], v[132:133], v[44:45]
	v_pk_mul_f32 v[46:47], v[130:131], v[56:57]
	s_waitcnt lgkmcnt(2)
	v_pk_mul_f32 v[134:135], v[132:133], v[50:51]
	v_cvt_pk_bf16_f32 v46, v46, v47
	v_cvt_pk_bf16_f32 v47, v2, v3
	v_pk_mul_f32 v[2:3], v[132:133], v[116:117]
	v_cvt_pk_bf16_f32 v52, v52, v53
	v_cvt_pk_bf16_f32 v53, v2, v3
	v_add_u32_e32 v2, 8, v145
	ds_write2st64_b64 v2, v[46:47], v[52:53] offset0:49 offset1:67
	v_pk_mul_f32 v[2:3], v[134:135], v[44:45]
	v_pk_mul_f32 v[44:45], v[126:127], v[56:57]
	v_pk_mul_f32 v[52:53], v[126:127], v[118:119]
	v_pk_mul_f32 v[46:47], v[134:135], v[116:117]
	v_cvt_pk_bf16_f32 v44, v44, v52
	v_cvt_pk_bf16_f32 v45, v45, v53
	v_add_u32_e32 v52, 0x1000, v223
	ds_write2_b32 v52, v44, v45 offset0:64 offset1:132
	v_cvt_pk_bf16_f32 v2, v2, v46
	v_cvt_pk_bf16_f32 v3, v3, v47
	v_add_u32_e32 v44, 0x1200, v223
	ds_write2_b32 v44, v2, v3 offset0:72 offset1:140
	s_and_saveexec_b64 s[24:25], s[60:61]
	ds_write_b128 v181, v[48:51] offset:64
	s_or_b64 exec, exec, s[24:25]
	s_and_saveexec_b64 s[24:25], s[72:73]
	s_cbranch_execz .LBB0_174
	v_mov_b32_e32 v1, v75
	s_nop 1
	v_permlane16_swap_b32_e32 v75, v1
	v_add_f32_e32 v1, v75, v1
	v_mov_b32_e32 v2, v1
	s_nop 1
	v_permlane32_swap_b32_e32 v1, v2
	s_and_b64 exec, exec, s[48:49]
	s_cbranch_execz .LBB0_174
	v_lshlrev_b64 v[44:45], 6, v[94:95]
	v_lshl_add_u64 v[44:45], v[82:83], 0, v[44:45]
	s_waitcnt lgkmcnt(0)
	v_add_f32_e32 v1, v1, v2
	global_store_dword v[44:45], v1, off

; #define LAS __attribute__((address_space(3)))
; __device__ __forceinline__ void rw_scan(LAS unsigned char* L, const bf16_t* Rg, const bf16_t* Kg, const bf16_t* Vg, const bf16_t* VF, const bf16_t* LO, const bf16_t* wlbT, const bf16_t* albT, const bf16_t* vlbT, ...
;     ...
;             if (m >= 2) {
;                 const LAS bf16_t* ob = OUTb + (m & 1) * (64 * 18);
;                 const int i = tid >> 3, rr = (tid & 7) * 2; const int st = 64 * (m - 2) + i, t = g ? (S_ - 1 - st) : st; const size_t row = (size_t)b * S_ + t;
;                 *(unsigned*)(WKV + ((size_t)g * T_ + row) * 1024 + h * 64 + 16 * q + rr) = *(const LAS unsigned*)(ob + i * 18 + rr);
.LBB0_180:
	s_or_b64 exec, exec, s[24:25]
	s_andn2_b64 vcc, exec, s[22:23]
	s_cbranch_vccnz .LBB0_182
	v_lshl_add_u32 v1, s26, 6, v142
	s_waitcnt lgkmcnt(0)
	v_sub_u32_e32 v2, 0x3fff, v1
	v_cndmask_b32_e64 v2, v2, v1, s[70:71]
	v_ashrrev_i32_e32 v3, 31, v2
	v_lshl_add_u64 v[2:3], v[2:3], 0, s[38:39]
	v_lshlrev_b64 v[2:3], 11, v[2:3]
	v_lshl_add_u64 v[2:3], v[84:85], 0, v[2:3]
	global_store_dword v[2:3], v250, off
